# scan recurrence loop + rownorm row loop + attention ck prefetch scaling + gMLP gating group loop rewritten by hand; scan LDS waits bounded
# speedup vs baseline: 1.0053x; 1.0053x over previous
; #define LAS __attribute__((address_space(3)))
; __device__ __forceinline__ void scan_unit(ArgsK& a, LAS unsigned char* lds, int u, int tid, int wave, int lane) {
;     ...
;     if (!scanw) { SCAN_LOAD_RAW(0); SCAN_PREP(0); if (SC_T < T) SCAN_LOAD_RAW(SC_T); }
;     __syncthreads();
;     for (int c = 0; c < NC; ++c) {
;         const int t0 = c * SC_T, nt = (T - t0) < SC_T ? (T - t0) : SC_T;
;         if (scanw) {
;             LAS float* Bc = L0 + (c & 1) * SC_SET;
;             ScanOps oA, oB; f32x2 vA2, vB2;
;             SCAN_LD(oA, vA2, Bc, 0);
;             for (int tt = 0; tt < nt; tt += 2) {
;                 SCAN_LD(oB, vB2, Bc, tt + 1);
;                 SCAN_STEP(oA, vA2, Bc, tt);
;                 { const int tn = (tt + 2 < nt) ? tt + 2 : tt; SCAN_LD(oA, vA2, Bc, tn); }
;                 SCAN_STEP(oB, vB2, Bc, tt + 1);
;             }
.Lscan4_loop:
	s_waitcnt lgkmcnt(12)
	v_pk_mul_f32 v[104:105], v[12:13], v[20:21]
	v_pk_mul_f32 v[106:107], v[4:5], v[20:21]
	v_add_f32_dpp v130, v130, v130 quad_perm:[1,0,3,2] row_mask:0xf bank_mask:0xf bound_ctrl:1
	v_add_f32_dpp v131, v131, v131 quad_perm:[1,0,3,2] row_mask:0xf bank_mask:0xf bound_ctrl:1
	v_pk_mul_f32 v[110:111], v[44:45], v[60:61] op_sel_hi:[1,0]
	v_pk_mul_f32 v[118:119], v[44:45], v[60:61] op_sel:[0,1]
	v_pk_fma_f32 v[104:105], v[14:15], v[22:23], v[104:105]
	v_pk_fma_f32 v[106:107], v[6:7], v[22:23], v[106:107]
	v_add_f32_dpp v130, v130, v130 quad_perm:[2,3,0,1] row_mask:0xf bank_mask:0xf bound_ctrl:1
	v_add_f32_dpp v131, v131, v131 quad_perm:[2,3,0,1] row_mask:0xf bank_mask:0xf bound_ctrl:1
	v_pk_mul_f32 v[112:113], v[46:47], v[60:61] op_sel_hi:[1,0]
	v_pk_mul_f32 v[120:121], v[46:47], v[60:61] op_sel:[0,1]
	v_pk_fma_f32 v[104:105], v[16:17], v[24:25], v[104:105]
	v_pk_fma_f32 v[106:107], v[8:9], v[24:25], v[106:107]
	v_add_f32_dpp v130, v130, v130 row_half_mirror row_mask:0xf bank_mask:0xf bound_ctrl:1
	v_add_f32_dpp v131, v131, v131 row_half_mirror row_mask:0xf bank_mask:0xf bound_ctrl:1
	v_pk_mul_f32 v[114:115], v[48:49], v[60:61] op_sel_hi:[1,0]
	v_pk_mul_f32 v[122:123], v[48:49], v[60:61] op_sel:[0,1]
	v_pk_fma_f32 v[104:105], v[18:19], v[26:27], v[104:105]
	v_pk_fma_f32 v[106:107], v[10:11], v[26:27], v[106:107]
	ds_write_b64 v134, v[130:131]
	v_pk_mul_f32 v[116:117], v[50:51], v[60:61] op_sel_hi:[1,0]
	v_pk_mul_f32 v[124:125], v[50:51], v[60:61] op_sel:[0,1]
	s_waitcnt lgkmcnt(1)
	ds_read_b128 v[20:23], v132 offset:33280
	ds_read_b128 v[24:27], v132 offset:33296
	ds_read_b128 v[44:47], v132 offset:16896
	ds_read_b128 v[48:51], v132 offset:16912
	ds_read_b64 v[60:61], v133 offset:512
	v_add_f32_e32 v108, v104, v105
	v_add_f32_e32 v109, v106, v107
	v_pk_fma_f32 v[110:111], v[12:13], v[28:29], v[110:111]
	v_pk_fma_f32 v[118:119], v[4:5], v[28:29], v[118:119]
	v_add_f32_dpp v108, v108, v108 quad_perm:[1,0,3,2] row_mask:0xf bank_mask:0xf bound_ctrl:1
	v_add_f32_dpp v109, v109, v109 quad_perm:[1,0,3,2] row_mask:0xf bank_mask:0xf bound_ctrl:1
	v_pk_fma_f32 v[112:113], v[14:15], v[30:31], v[112:113]
	v_pk_fma_f32 v[120:121], v[6:7], v[30:31], v[120:121]
	v_add_f32_dpp v108, v108, v108 quad_perm:[2,3,0,1] row_mask:0xf bank_mask:0xf bound_ctrl:1
	v_add_f32_dpp v109, v109, v109 quad_perm:[2,3,0,1] row_mask:0xf bank_mask:0xf bound_ctrl:1
	v_pk_fma_f32 v[114:115], v[16:17], v[32:33], v[114:115]
	v_pk_fma_f32 v[122:123], v[8:9], v[32:33], v[122:123]
	v_add_f32_dpp v108, v108, v108 row_half_mirror row_mask:0xf bank_mask:0xf bound_ctrl:1
	v_add_f32_dpp v109, v109, v109 row_half_mirror row_mask:0xf bank_mask:0xf bound_ctrl:1
	v_pk_fma_f32 v[116:117], v[18:19], v[34:35], v[116:117]
	v_pk_fma_f32 v[124:125], v[10:11], v[34:35], v[124:125]
	ds_read_b128 v[28:31], v132 offset:8704
	ds_read_b128 v[32:35], v132 offset:8720
	v_pk_fma_f32 v[12:13], v[36:37], v[108:109], v[110:111] op_sel_hi:[1,0,1]
	v_pk_fma_f32 v[4:5], v[36:37], v[108:109], v[118:119] op_sel:[0,1,0]
	v_pk_fma_f32 v[14:15], v[38:39], v[108:109], v[112:113] op_sel_hi:[1,0,1]
	v_pk_fma_f32 v[6:7], v[38:39], v[108:109], v[120:121] op_sel:[0,1,0]
	v_pk_fma_f32 v[16:17], v[40:41], v[108:109], v[114:115] op_sel_hi:[1,0,1]
	v_pk_fma_f32 v[8:9], v[40:41], v[108:109], v[122:123] op_sel:[0,1,0]
	v_pk_fma_f32 v[18:19], v[42:43], v[108:109], v[116:117] op_sel_hi:[1,0,1]
	v_pk_fma_f32 v[10:11], v[42:43], v[108:109], v[124:125] op_sel:[0,1,0]
	ds_read_b128 v[36:39], v132 offset:41472
	ds_read_b128 v[40:43], v132 offset:41488
	v_pk_mul_f32 v[126:127], v[12:13], v[52:53]
	v_pk_mul_f32 v[128:129], v[4:5], v[52:53]
	v_pk_fma_f32 v[126:127], v[14:15], v[54:55], v[126:127]
	v_pk_fma_f32 v[128:129], v[6:7], v[54:55], v[128:129]
	v_pk_fma_f32 v[126:127], v[16:17], v[56:57], v[126:127]
	v_pk_fma_f32 v[128:129], v[8:9], v[56:57], v[128:129]
	v_pk_fma_f32 v[126:127], v[18:19], v[58:59], v[126:127]
	v_pk_fma_f32 v[128:129], v[10:11], v[58:59], v[128:129]
	ds_read_b128 v[52:55], v132 offset:512
	ds_read_b128 v[56:59], v132 offset:528
	v_add_f32_e32 v130, v126, v127
	v_add_f32_e32 v131, v128, v129
	s_waitcnt lgkmcnt(12)
; #define LAS __attribute__((address_space(3)))
; __device__ __forceinline__ void scan_unit(ArgsK& a, LAS unsigned char* lds, int u, int tid, int wave, int lane) {
;     ...
;     if (!scanw) { SCAN_LOAD_RAW(0); SCAN_PREP(0); if (SC_T < T) SCAN_LOAD_RAW(SC_T); }
;     __syncthreads();
;     for (int c = 0; c < NC; ++c) {
;         const int t0 = c * SC_T, nt = (T - t0) < SC_T ? (T - t0) : SC_T;
;         if (scanw) {
;             LAS float* Bc = L0 + (c & 1) * SC_SET;
;             ScanOps oA, oB; f32x2 vA2, vB2;
;             SCAN_LD(oA, vA2, Bc, 0);
;             for (int tt = 0; tt < nt; tt += 2) {
;                 SCAN_LD(oB, vB2, Bc, tt + 1);
;                 SCAN_STEP(oA, vA2, Bc, tt);
;                 { const int tn = (tt + 2 < nt) ? tt + 2 : tt; SCAN_LD(oA, vA2, Bc, tn); }
;                 SCAN_STEP(oB, vB2, Bc, tt + 1);
;             }
	v_pk_mul_f32 v[104:105], v[12:13], v[62:63]
	v_pk_mul_f32 v[106:107], v[4:5], v[62:63]
	v_add_f32_dpp v130, v130, v130 quad_perm:[1,0,3,2] row_mask:0xf bank_mask:0xf bound_ctrl:1
	v_add_f32_dpp v131, v131, v131 quad_perm:[1,0,3,2] row_mask:0xf bank_mask:0xf bound_ctrl:1
	v_pk_mul_f32 v[110:111], v[86:87], v[102:103] op_sel_hi:[1,0]
	v_pk_mul_f32 v[118:119], v[86:87], v[102:103] op_sel:[0,1]
	v_pk_fma_f32 v[104:105], v[14:15], v[64:65], v[104:105]
	v_pk_fma_f32 v[106:107], v[6:7], v[64:65], v[106:107]
	v_add_f32_dpp v130, v130, v130 quad_perm:[2,3,0,1] row_mask:0xf bank_mask:0xf bound_ctrl:1
	v_add_f32_dpp v131, v131, v131 quad_perm:[2,3,0,1] row_mask:0xf bank_mask:0xf bound_ctrl:1
	v_pk_mul_f32 v[112:113], v[88:89], v[102:103] op_sel_hi:[1,0]
	v_pk_mul_f32 v[120:121], v[88:89], v[102:103] op_sel:[0,1]
	v_pk_fma_f32 v[104:105], v[16:17], v[66:67], v[104:105]
	v_pk_fma_f32 v[106:107], v[8:9], v[66:67], v[106:107]
	v_add_f32_dpp v130, v130, v130 row_half_mirror row_mask:0xf bank_mask:0xf bound_ctrl:1
	v_add_f32_dpp v131, v131, v131 row_half_mirror row_mask:0xf bank_mask:0xf bound_ctrl:1
	v_pk_mul_f32 v[114:115], v[90:91], v[102:103] op_sel_hi:[1,0]
	v_pk_mul_f32 v[122:123], v[90:91], v[102:103] op_sel:[0,1]
	v_pk_fma_f32 v[104:105], v[18:19], v[68:69], v[104:105]
	v_pk_fma_f32 v[106:107], v[10:11], v[68:69], v[106:107]
	ds_write_b64 v133, v[130:131] offset:24576
	v_pk_mul_f32 v[116:117], v[92:93], v[102:103] op_sel_hi:[1,0]
	v_pk_mul_f32 v[124:125], v[92:93], v[102:103] op_sel:[0,1]
	s_waitcnt lgkmcnt(1)
	ds_read_b128 v[62:65], v132 offset:33536
	ds_read_b128 v[66:69], v132 offset:33552
	ds_read_b128 v[86:89], v132 offset:17152
	ds_read_b128 v[90:93], v132 offset:17168
	ds_read_b64 v[102:103], v133 offset:768
	v_add_f32_e32 v108, v104, v105
	v_add_f32_e32 v109, v106, v107
	v_pk_fma_f32 v[110:111], v[12:13], v[70:71], v[110:111]
	v_pk_fma_f32 v[118:119], v[4:5], v[70:71], v[118:119]
	v_add_f32_dpp v108, v108, v108 quad_perm:[1,0,3,2] row_mask:0xf bank_mask:0xf bound_ctrl:1
	v_add_f32_dpp v109, v109, v109 quad_perm:[1,0,3,2] row_mask:0xf bank_mask:0xf bound_ctrl:1
	v_pk_fma_f32 v[112:113], v[14:15], v[72:73], v[112:113]
	v_pk_fma_f32 v[120:121], v[6:7], v[72:73], v[120:121]
	v_add_f32_dpp v108, v108, v108 quad_perm:[2,3,0,1] row_mask:0xf bank_mask:0xf bound_ctrl:1
	v_add_f32_dpp v109, v109, v109 quad_perm:[2,3,0,1] row_mask:0xf bank_mask:0xf bound_ctrl:1
	v_pk_fma_f32 v[114:115], v[16:17], v[74:75], v[114:115]
	v_pk_fma_f32 v[122:123], v[8:9], v[74:75], v[122:123]
	v_add_f32_dpp v108, v108, v108 row_half_mirror row_mask:0xf bank_mask:0xf bound_ctrl:1
	v_add_f32_dpp v109, v109, v109 row_half_mirror row_mask:0xf bank_mask:0xf bound_ctrl:1
	v_pk_fma_f32 v[116:117], v[18:19], v[76:77], v[116:117]
	v_pk_fma_f32 v[124:125], v[10:11], v[76:77], v[124:125]
	ds_read_b128 v[70:73], v132 offset:8960
	ds_read_b128 v[74:77], v132 offset:8976
	v_pk_fma_f32 v[12:13], v[78:79], v[108:109], v[110:111] op_sel_hi:[1,0,1]
	v_pk_fma_f32 v[4:5], v[78:79], v[108:109], v[118:119] op_sel:[0,1,0]
	v_pk_fma_f32 v[14:15], v[80:81], v[108:109], v[112:113] op_sel_hi:[1,0,1]
	v_pk_fma_f32 v[6:7], v[80:81], v[108:109], v[120:121] op_sel:[0,1,0]
	v_pk_fma_f32 v[16:17], v[82:83], v[108:109], v[114:115] op_sel_hi:[1,0,1]
	v_pk_fma_f32 v[8:9], v[82:83], v[108:109], v[122:123] op_sel:[0,1,0]
	v_pk_fma_f32 v[18:19], v[84:85], v[108:109], v[116:117] op_sel_hi:[1,0,1]
	v_pk_fma_f32 v[10:11], v[84:85], v[108:109], v[124:125] op_sel:[0,1,0]
	ds_read_b128 v[78:81], v132 offset:41728
	ds_read_b128 v[82:85], v132 offset:41744
	v_pk_mul_f32 v[126:127], v[12:13], v[94:95]
	v_pk_mul_f32 v[128:129], v[4:5], v[94:95]
	v_pk_fma_f32 v[126:127], v[14:15], v[96:97], v[126:127]
	v_pk_fma_f32 v[128:129], v[6:7], v[96:97], v[128:129]
	v_pk_fma_f32 v[126:127], v[16:17], v[98:99], v[126:127]
	v_pk_fma_f32 v[128:129], v[8:9], v[98:99], v[128:129]
	v_pk_fma_f32 v[126:127], v[18:19], v[100:101], v[126:127]
	v_pk_fma_f32 v[128:129], v[10:11], v[100:101], v[128:129]
	ds_read_b128 v[94:97], v132 offset:768
	ds_read_b128 v[98:101], v132 offset:784
	v_add_f32_e32 v130, v126, v127
	v_add_f32_e32 v131, v128, v129
	v_add_u32_e32 v132, 0x200, v132
	v_add_u32_e32 v133, 0x200, v133
	s_add_i32 s6, s6, 2
	v_add_u32_e32 v134, 0x5f00, v133
	s_cmp_lt_i32 s6, s5
	s_cbranch_scc1 .Lscan4_loop
	s_nop 1
	v_add_f32_dpp v130, v130, v130 quad_perm:[1,0,3,2] row_mask:0xf bank_mask:0xf bound_ctrl:1
	v_add_f32_dpp v131, v131, v131 quad_perm:[1,0,3,2] row_mask:0xf bank_mask:0xf bound_ctrl:1
	s_nop 1
	v_add_f32_dpp v130, v130, v130 quad_perm:[2,3,0,1] row_mask:0xf bank_mask:0xf bound_ctrl:1
	v_add_f32_dpp v131, v131, v131 quad_perm:[2,3,0,1] row_mask:0xf bank_mask:0xf bound_ctrl:1
	s_nop 1
	v_add_f32_dpp v130, v130, v130 row_half_mirror row_mask:0xf bank_mask:0xf bound_ctrl:1
	v_add_f32_dpp v131, v131, v131 row_half_mirror row_mask:0xf bank_mask:0xf bound_ctrl:1
	s_nop 0
	ds_write_b64 v134, v[130:131]
	s_branch .LBB0_205
